# layer-0 scan: non-delta long-item workgroups (GLA, HGRN, retention) convert the last 1504 weight tiles after their item; secondaries convert 22 tiles each instead of 30
# baseline (speedup 1.0000x reference)
; __device__ __forceinline__ void scan_phase(const Params& p, int layer, char* lds, int bid, int nb, const int tid, const int role, const int ci, const int nprim, const int nsec) {
;     ...
;   if (paired) {
;     int u = -1;
;     if (role == 0) u = ci; else if (ci < NPI - 256) u = 256 + ci;
;     if (u >= 0) { int b; const int type = long_item_type(u, b); scan_dispatch(p, layer, 0, type, b, 1, b + 1, lds, tid); }
;     else { j = ci - (NPI - 256); nbs = 256 - (NPI - 256); }
;   } else {
;     for (int u = bid; u < NPI; u += nb) { int b; const int type = long_item_type(u, b); scan_dispatch(p, layer, 0, type, b, 1, b + 1, lds, tid); }
;     nbs = (nb > NPI) ? nb - NPI : nb; j = (nb > NPI) ? bid - NPI : bid;
;   }
;   if (j >= 0) {
;     const int nsl = (nbs + ITEMS_PER_SEQ - 1) / ITEMS_PER_SEQ;
;     for (int jj = j; jj < ITEMS_PER_SEQ * nsl; jj += nbs) scan_dispatch(p, layer, 1, jj % ITEMS_PER_SEQ, jj / ITEMS_PER_SEQ, nsl, NSB, lds, tid);
;     if (layer == 0) { __syncthreads(); convert_weights(p, lds, 992 + j, 6720, nbs, tid); }
.LBB0_450:
	s_cmp_lg_u32 s64, 2
	s_cbranch_scc1 .Lhlp_no
	v_readlane_b32 s2, v254, 15
	v_readlane_b32 s3, v254, 16
	s_nop 3
	s_cmpk_lg_i32 s2, 0x100
	s_cbranch_scc1 .Lhlp_no
	s_cmpk_lg_i32 s3, 0x100
	s_cbranch_scc1 .Lhlp_no
	v_readlane_b32 s2, v252, 6
	v_readlane_b32 s3, v252, 2
	s_nop 3
	s_cmp_lg_u32 s3, 0
	s_cbranch_scc1 .Lhlp_ret
	s_cmpk_lt_i32 s2, 64
	s_cbranch_scc1 .Lhlp_go
	s_cmpk_lt_i32 s2, 0xc0
	s_cbranch_scc1 .Lhlp_no
	s_sub_i32 s2, s2, 0x80
	s_branch .Lhlp_go
.Lhlp_ret:
	s_cmpk_ge_i32 s2, 64
	s_cbranch_scc1 .Lhlp_no
	s_addk_i32 s2, 0x80
.Lhlp_go:
	s_addk_i32 s2, 0x1080
	s_movk_i32 s52, 0xc0
	v_writelane_b32 v255, s2, 10
	v_writelane_b32 v255, s52, 12
	s_add_i32 s23, s64, 6
	s_branch .LBB0_577

; __device__ __forceinline__ void convert_weights(const Params& p, char* lds, int w0, int w1, int wstep, const int tid) {
;     ...
;   for (int w = w0; w < w1; w += wstep) {
; __device__ __forceinline__ void scan_phase(const Params& p, int layer, char* lds, int bid, int nb, const int tid, const int role, const int ci, const int nprim, const int nsec) {
;     ...
;     if (layer == 0) { __syncthreads(); convert_weights(p, lds, 992 + j, 6720, nbs, tid); }
.LBB0_577:
	s_movk_i32 s83, 0x1a3f
	s_cmp_lg_u32 s64, 2
	s_cbranch_scc1 .Lhlp_b
	v_readlane_b32 s2, v254, 15
	v_readlane_b32 s3, v254, 16
	s_nop 3
	s_cmpk_lg_i32 s2, 0x100
	s_cbranch_scc1 .Lhlp_b
	s_cmpk_lg_i32 s3, 0x100
	s_cbranch_scc1 .Lhlp_b
	v_readlane_b32 s82, v255, 10
	s_nop 3
	s_cmpk_ge_i32 s82, 0xc0
	s_cbranch_scc1 .Lhlp_b
	s_movk_i32 s83, 0x145f

;   __device__ __forceinline__ unsigned char* W() const { return (unsigned char*)(GAS unsigned char*)ws; }
; __device__ __forceinline__ unsigned pk2(float lo, float hi) { const f32x2_t v = {lo, hi}; const bf16x2_t b = __builtin_convertvector(v, bf16x2_t); return __builtin_bit_cast(unsigned, b); }
; __device__ __forceinline__ void convert_weights(const Params& p, char* lds, int w0, int w1, int wstep, const int tid) {
;     ...
;       const int rr = tid >> 2, kc = (tid & 3) * 16;
;       const int Kd = (mat == 3) ? DFF : 1024;
;       bf16_t* base;
;       if (mat == 0) base = (bf16_t*)(p.W() + OFF_WIN + l * SZ_WIN);
;       else if (mat == 1) base = (bf16_t*)(p.W() + OFF_WOUT + l * SZ_WOUT);
;       else if (mat == 2) base = (bf16_t*)(p.W() + OFF_WGU + l * SZ_WGU);
;       else base = (bf16_t*)(p.W() + OFF_WDN + l * SZ_WDN);
;       bf16_t* dst = base + (size_t)(rt * 64 + rr) * Kd + kt * 64 + kc;
;       const float* s = tile + rr * 65 + kc;
;       uint4 a, b;
;       a.x = pk2(s[0], s[1]); a.y = pk2(s[2], s[3]); a.z = pk2(s[4], s[5]); a.w = pk2(s[6], s[7]);
;       b.x = pk2(s[8], s[9]); b.y = pk2(s[10], s[11]); b.z = pk2(s[12], s[13]); b.w = pk2(s[14], s[15]);
;       *(uint4*)dst = a; *(uint4*)(dst + 8) = b;
;     }
;     __syncthreads();
.LBB0_580:
	v_add_u32_e32 v4, s24, v24
	v_ashrrev_i32_e32 v5, 31, v4
	v_mul_lo_u32 v6, s34, v5
	v_mul_lo_u32 v7, s35, v4
	v_mad_u64_u32 v[4:5], s[2:3], s34, v4, 0
	v_add3_u32 v5, v5, v6, v7
	v_lshl_add_u64 v[4:5], v[4:5], 1, s[36:37]
	s_ashr_i32 s43, s42, 31
	v_lshl_add_u64 v[4:5], s[42:43], 1, v[4:5]
	v_lshl_add_u64 v[12:13], v[4:5], 0, v[2:3]
	ds_read2_b32 v[4:5], v25 offset1:1
	ds_read2_b32 v[6:7], v25 offset0:2 offset1:3
	ds_read2_b32 v[8:9], v25 offset0:6 offset1:7
	ds_read2_b32 v[14:15], v25 offset0:14 offset1:15
	ds_read2_b32 v[10:11], v25 offset0:10 offset1:11
	s_waitcnt lgkmcnt(4)
	v_cvt_pk_bf16_f32 v4, v4, v5
	s_waitcnt lgkmcnt(3)
	v_cvt_pk_bf16_f32 v5, v6, v7
	ds_read2_b32 v[6:7], v25 offset0:4 offset1:5
	s_add_i32 s23, s23, s52
	s_cmp_gt_i32 s23, s83
	s_waitcnt lgkmcnt(0)
	v_cvt_pk_bf16_f32 v6, v6, v7
	v_cvt_pk_bf16_f32 v7, v8, v9
	ds_read2_b32 v[8:9], v25 offset0:8 offset1:9
	s_waitcnt lgkmcnt(0)
	v_cvt_pk_bf16_f32 v8, v8, v9
	v_cvt_pk_bf16_f32 v9, v10, v11
	ds_read2_b32 v[10:11], v25 offset0:12 offset1:13
	s_waitcnt lgkmcnt(0)
	v_cvt_pk_bf16_f32 v10, v10, v11
	v_cvt_pk_bf16_f32 v11, v14, v15
	global_store_dwordx4 v[12:13], v[4:7], off
	global_store_dwordx4 v[12:13], v[8:11], off offset:16
	s_barrier
	s_cbranch_scc1 .LBB0_623
